# k9 plus stick-breaking attention prologue de-serialised: tile-1 K/V loads issued together with tile-0 loads into registers that are dead in the prologue
# baseline (speedup 1.0000x reference)
; #define TID() (wv0 * 64 + (int)__builtin_amdgcn_mbcnt_hi(~0u, __builtin_amdgcn_mbcnt_lo(~0u, 0u)))
; __device__ __forceinline__ int opaque(int x) { asm volatile("" : "+v"(x)); return x; }
; __device__ __forceinline__ int v_st(int k, int c) { const int kk = (k & ~0xC) | ((k & 4) << 1) | ((k & 8) >> 1); return ((kk >> 3) * 4 + (c >> 5)) * 512 + ((kk & 7) * 32 + (c & 31)) * 2; }
; __device__ __forceinline__ int v_rd_base(int lane) { return ((lane & 3) << 3) | (((lane >> 2) & 3) << 6) | (((lane >> 4) & 1) << 5) | (((lane >> 5) & 1) << 8); }
; #define SLOAD(i, k0) do { sr_[i].vs0 = *reinterpret_cast<const bf16x8*>(&Vh[(size_t)((k0) + sr) * LD + sc]); sr_[i].vs1 = *reinterpret_cast<const bf16x8*>(&Vh[(size_t)((k0) + 32 + sr) * LD + sc]); \
;     sr_[i].ks0 = *reinterpret_cast<const bf16x8*>(&Kh[(size_t)((k0) + sr) * LD + sc]); sr_[i].ks1 = *reinterpret_cast<const bf16x8*>(&Kh[(size_t)((k0) + 32 + sr) * LD + sc]); } while (0)
; #define SWAIT() asm volatile("s_waitcnt vmcnt(0)" ::: "memory")
; __device__ __forceinline__ void sb_unit(const bf16* __restrict__ Qb, const bf16* __restrict__ Kh, const bf16* __restrict__ Vh, bf16* __restrict__ Ob, int q0, char* lds, const int wv0) {
;     const int tid = opaque(TID()), wid = tid >> 6, lane = tid & 63, r32 = lane & 31, hi = lane >> 5;
;     char* V_lds = lds; char* K_lds = lds + 2 * SHM_V;
;     const int NT = (q0 + 256) / KVBLK;
;     f32x16 o[4] = {}; bf16x8 qr[8];
;     const int tq = q0 + wid * 32 + r32;
;     const bf16* Qw = Qb + (size_t)tq * LD + hi * 8;
; #pragma unroll
;     for (int d0 = 0; d0 < 8; ++d0) qr[d0] = *reinterpret_cast<const bf16x8*>(Qw + d0 * 16);
;     const int sr = tid >> 4, sc = (tid & 15) * 8, vst0 = v_st(sr, sc), vst1 = v_st(32 + sr, sc);
;     const int vb0 = (int)(uintptr_t)V_lds + v_rd_base(lane);
;     struct { bf16x8 vs0, vs1, ks0, ks1; } sr_[1];
;     ...
;     f32x16 pA0, pA1, pB0, pB1; bf16x8 pa0, pa1, pa2, pa3; float carry = 1.0f;
;     constexpr int SE = 0, SO = 0;
;     __syncthreads();
;     SLOAD(SE, K0(0)); asm volatile("s_waitcnt vmcnt(0)" ::: "memory"); SWRITE(0, SE); __syncthreads();
;     qkt(pA0, pA1, K_lds, qr, r32, hi); sb_half(pA1, carry, true, K0(0) + 32, tq, hi);
;     SLOAD(SO, K0(1));
;     SWAIT(); SWRITE(1, SO); __syncthreads();
.LBB0_284:
	s_xor_b64 s[60:61], s[0:1], -1
	s_and_b64 s[0:1], s[0:1], exec
	v_mov_b32_e32 v16, v204
	s_cselect_b32 s95, s94, s93
	s_add_i32 s1, s95, 0x100
	v_ashrrev_i32_e32 v18, 6, v16
	v_and_b32_e32 v253, 31, v16
	v_lshl_add_u32 v162, v18, 5, s95
	v_or_b32_e32 v164, v162, v253
	v_ashrrev_i32_e32 v165, 31, v164
	v_bfe_u32 v252, v16, 5, 1
	v_lshlrev_b64 v[0:1], 11, v[164:165]
	v_lshl_add_u64 v[0:1], s[50:51], 0, v[0:1]
	v_lshlrev_b32_e32 v160, 4, v252
	s_lshr_b32 s40, s1, 6
	v_lshl_add_u64 v[0:1], v[0:1], 0, v[160:161]
	v_lshlrev_b32_e32 v19, 3, v16
	s_cmp_lg_u32 0, -1
	global_load_dwordx4 v[140:143], v[0:1], off
	global_load_dwordx4 v[136:139], v[0:1], off offset:32
	global_load_dwordx4 v[132:135], v[0:1], off offset:64
	global_load_dwordx4 v[128:131], v[0:1], off offset:96
	global_load_dwordx4 v[124:127], v[0:1], off offset:128
	global_load_dwordx4 v[120:123], v[0:1], off offset:160
	global_load_dwordx4 v[116:119], v[0:1], off offset:192
	global_load_dwordx4 v[112:115], v[0:1], off offset:224
	v_ashrrev_i32_e32 v17, 4, v16
	v_and_b32_e32 v0, 0x78, v19
	s_cselect_b32 s18, 0, 0
	s_add_i32 s0, s95, 0xc0
	v_lshlrev_b32_e32 v30, 1, v0
	v_add_u32_e32 v0, s0, v17
	v_ashrrev_i32_e32 v1, 31, v0
	s_add_i32 s0, s95, 0xe0
	v_lshlrev_b64 v[8:9], 11, v[0:1]
	v_add_u32_e32 v0, s0, v17
	v_ashrrev_i32_e32 v1, 31, v0
	v_lshlrev_b64 v[12:13], 11, v[0:1]
	v_or_b32_e32 v8, v8, v30
	v_or_b32_e32 v12, v12, v30
	v_lshl_add_u64 v[10:11], s[54:55], 0, v[8:9]
	v_lshl_add_u64 v[14:15], s[54:55], 0, v[12:13]
	v_lshl_add_u64 v[20:21], s[52:53], 0, v[8:9]
	s_waitcnt vmcnt(63) expcnt(7) lgkmcnt(15)
	s_barrier
	global_load_dwordx4 v[0:3], v[10:11], off
	global_load_dwordx4 v[4:7], v[14:15], off
	v_lshl_add_u64 v[22:23], s[52:53], 0, v[12:13]
	global_load_dwordx4 v[8:11], v[20:21], off
	global_load_dwordx4 v[12:15], v[22:23], off
	v_and_b32_e32 v21, 0xfffff0, v17
	v_lshlrev_b32_e32 v22, 1, v17
	v_lshrrev_b32_e32 v23, 1, v17
	v_and_b32_e32 v24, 3, v17
	v_add_u32_e32 v25, 32, v17
	v_and_or_b32 v21, v22, 8, v21
	v_and_or_b32 v22, v23, 4, v24
	v_and_b32_e32 v23, 0xfffff0, v25
	v_lshlrev_b32_e32 v24, 1, v25
	v_and_b32_e32 v20, 0x70, v16
	v_bfe_u32 v19, v19, 5, 2
	v_lshlrev_b32_e32 v26, 8, v17
	v_lshlrev_b32_e32 v25, 8, v25
	v_lshrrev_b32_e32 v21, 1, v21
	v_and_or_b32 v23, v24, 8, v23
	v_bitop3_b32 v24, v30, v26, v20 bitop3:0xde
	v_bitop3_b32 v20, v30, v25, v20 bitop3:0xde
	v_or_b32_e32 v21, v21, v19
	v_lshrrev_b32_e32 v23, 1, v23
	v_lshlrev_b32_e32 v22, 6, v22
	v_and_b32_e32 v27, 48, v30
	v_add_u32_e32 v200, 0, v20
	v_lshlrev_b32_e32 v20, 9, v21
	v_or_b32_e32 v19, v23, v19
	v_lshlrev_b32_e32 v44, 4, v16
	v_or3_b32 v20, v20, v22, v27
	v_lshlrev_b32_e32 v19, 9, v19
	v_lshlrev_b32_e32 v29, 8, v253
	v_and_b32_e32 v31, 0x70, v44
	v_or3_b32 v19, v19, v22, v27
	v_add_u32_e32 v206, 0, v20
	v_add_u32_e32 v199, 0, v24
	v_add_u32_e32 v207, 0, v19
	s_mov_b32 s2, 0xfffd0000
	s_mov_b32 s3, -1
	v_add_u32_e32 v146, s1, v17
	v_ashrrev_i32_e32 v147, 31, v146
	v_lshlrev_b64 v[146:147], 11, v[146:147]
	v_or_b32_e32 v146, v146, v30
	v_lshl_add_u64 v[150:151], v[146:147], 0, s[2:3]
	v_lshl_add_u64 v[146:147], v[146:147], 0, s[48:49]
	v_lshl_add_u64 v[144:145], s[54:55], 0, v[146:147]
	v_lshl_add_u64 v[152:153], s[52:53], 0, v[146:147]
	v_lshl_add_u64 v[148:149], s[54:55], 0, v[150:151]
	v_lshl_add_u64 v[156:157], s[52:53], 0, v[150:151]
	global_load_dwordx4 v[144:147], v[144:145], off
	global_load_dwordx4 v[148:151], v[148:149], off
	global_load_dwordx4 v[152:155], v[152:153], off
	global_load_dwordx4 v[156:159], v[156:157], off
	s_waitcnt vmcnt(4)
	v_or_b32_e32 v19, 64, v160
	v_bitop3_b32 v19, v19, v29, v31 bitop3:0xde
	v_add_u32_e32 v208, 0, v19
	v_or_b32_e32 v19, 0x60, v160
	v_bitop3_b32 v19, v19, v29, v31 bitop3:0xde
	v_add_u32_e32 v209, 0, v19
	v_or_b32_e32 v19, 0x80, v160
	v_bitop3_b32 v19, v19, v29, v31 bitop3:0xde
	v_add_u32_e32 v210, 0, v19
	v_or_b32_e32 v19, 0xa0, v160
	v_bitop3_b32 v19, v19, v29, v31 bitop3:0xde
	v_add_u32_e32 v211, 0, v19
	v_or_b32_e32 v19, 0xc0, v160
	v_bitop3_b32 v19, v19, v29, v31 bitop3:0xde
	v_add_u32_e32 v203, 0, v19
	v_or_b32_e32 v19, 0xe0, v160
	v_add_u32_e32 v28, s1, v17
	v_bitop3_b32 v19, v19, v29, v31 bitop3:0xde
	s_mov_b32 s2, 0xfffd0000
	s_mov_b32 s3, -1
	s_waitcnt vmcnt(7)
	ds_write_b128 v206, v[0:3]
	s_waitcnt vmcnt(6)
	ds_write_b128 v207, v[4:7]
	s_waitcnt vmcnt(5)
	ds_write_b128 v199, v[8:11] offset:32768
	s_waitcnt vmcnt(4)
	ds_write_b128 v200, v[12:15] offset:32768
	v_bitop3_b32 v0, v160, v29, v31 bitop3:0xde
	v_add_u32_e32 v201, 0, v0
	s_waitcnt lgkmcnt(0)
	s_barrier
; __device__ __forceinline__ int crow(int r, int hi) { return (r & 3) + 8 * (r >> 2) + 4 * hi; }
; __device__ __forceinline__ void qkt(f32x16& p0, f32x16& p1, const char* Ks, const bf16x8* qr, int r32, int hi) {
;     p0 = f32x16{}; p1 = f32x16{};
; #pragma unroll
;     for (int d0 = 0; d0 < 8; ++d0) { const int cb = (d0 * 16 + hi * 8) * 2;
;         const bf16x8 b0 = *reinterpret_cast<const bf16x8*>(Ks + KSWZ(r32, cb));
;         const bf16x8 b1 = *reinterpret_cast<const bf16x8*>(Ks + KSWZ(32 + r32, cb));
;         p0 = __builtin_amdgcn_mfma_f32_32x32x16_bf16(b0, qr[d0], p0, 0, 0, 0);
;         p1 = __builtin_amdgcn_mfma_f32_32x32x16_bf16(b1, qr[d0], p1, 0, 0, 0); }
; __device__ __forceinline__ void sb_half(f32x16& p, float& carry, bool masked, int krow0, int tq, int hi) {
;     float G[4];
; #pragma unroll
;     for (int g = 0; g < 4; ++g) {
;         float q[4];
; #pragma unroll
;         for (int i = 0; i < 4; ++i) { const int r = 4 * g + i; const float e = __builtin_amdgcn_exp2f(p[r]); float qq = __builtin_amdgcn_rcpf(1.0f + e); float b = e * qq;
;             if (masked) { const bool keep = (krow0 + crow(r, hi)) < tq; qq = keep ? qq : 1.0f; b = keep ? b : 0.0f; }
;             q[i] = qq; p[r] = b; }
;         const float s2 = q[3] * q[2], s1 = s2 * q[1]; G[g] = s1 * q[0];
;         p[4 * g + 2] *= q[3]; p[4 * g + 1] *= s2; p[4 * g] *= s1;
	ds_read_b128 v[0:3], v201 offset:32768
	ds_read_b128 v[4:7], v201 offset:40960
	s_waitcnt lgkmcnt(1)
	v_mfma_f32_32x32x16_bf16 v[64:79], v[0:3], v[140:143], 0
	v_or_b32_e32 v0, 32, v160
	v_bitop3_b32 v0, v0, v29, v31 bitop3:0xde
	v_add_u32_e32 v202, 0, v0
	ds_read_b128 v[20:23], v202 offset:32768
	ds_read_b128 v[24:27], v202 offset:40960
	v_ashrrev_i32_e32 v29, 31, v28
	v_add_u32_e32 v212, 0, v19
	v_and_b32_e32 v19, 63, v16
	s_waitcnt lgkmcnt(2)
	v_mfma_f32_32x32x16_bf16 v[0:15], v[4:7], v[140:143], 0
	v_lshlrev_b32_e32 v45, 3, v19
	v_lshlrev_b32_e32 v163, 2, v252
	v_lshl_add_u32 v166, v18, 2, s90
	s_mov_b32 s41, 2
	v_mov_b32_e32 v167, s47
	v_add_u32_e32 v168, 32, v166
	v_mov_b32_e32 v169, s47
	s_waitcnt lgkmcnt(1)
	v_mfma_f32_32x32x16_bf16 v[64:79], v[20:23], v[136:139], v[64:79]
	s_mov_b64 s[62:63], 0
	v_mov_b32_e32 v213, v163
	s_waitcnt lgkmcnt(0)
	v_mfma_f32_32x32x16_bf16 v[0:15], v[24:27], v[136:139], v[0:15]
	ds_read_b128 v[20:23], v208 offset:32768
	ds_read_b128 v[24:27], v208 offset:40960
	s_waitcnt lgkmcnt(1)
	v_mfma_f32_32x32x16_bf16 v[64:79], v[20:23], v[132:135], v[64:79]
	s_waitcnt lgkmcnt(0)
	v_mfma_f32_32x32x16_bf16 v[0:15], v[24:27], v[132:135], v[0:15]
	ds_read_b128 v[20:23], v209 offset:32768
	ds_read_b128 v[24:27], v209 offset:40960
	s_waitcnt lgkmcnt(1)
	v_mfma_f32_32x32x16_bf16 v[64:79], v[20:23], v[128:131], v[64:79]
	s_waitcnt lgkmcnt(0)
	v_mfma_f32_32x32x16_bf16 v[0:15], v[24:27], v[128:131], v[0:15]
	ds_read_b128 v[20:23], v210 offset:32768
	ds_read_b128 v[24:27], v210 offset:40960
	s_waitcnt lgkmcnt(1)
	v_mfma_f32_32x32x16_bf16 v[64:79], v[20:23], v[124:127], v[64:79]
	s_waitcnt lgkmcnt(0)
	v_mfma_f32_32x32x16_bf16 v[0:15], v[24:27], v[124:127], v[0:15]
	ds_read_b128 v[20:23], v211 offset:32768
	ds_read_b128 v[24:27], v211 offset:40960
	s_waitcnt lgkmcnt(1)
	v_mfma_f32_32x32x16_bf16 v[64:79], v[20:23], v[120:123], v[64:79]
	ds_read_b128 v[20:23], v203 offset:32768
	s_waitcnt lgkmcnt(1)
	v_mfma_f32_32x32x16_bf16 v[0:15], v[24:27], v[120:123], v[0:15]
	ds_read_b128 v[24:27], v203 offset:40960
	s_waitcnt lgkmcnt(1)
	v_mfma_f32_32x32x16_bf16 v[64:79], v[20:23], v[116:119], v[64:79]
	v_lshlrev_b64 v[20:21], 11, v[28:29]
	v_or_b32_e32 v20, v20, v30
	v_lshl_add_u64 v[28:29], v[20:21], 0, s[48:49]
	v_lshl_add_u64 v[32:33], v[20:21], 0, s[2:3]
	v_lshl_add_u64 v[30:31], s[54:55], 0, v[28:29]
	v_lshl_add_u64 v[34:35], s[54:55], 0, v[32:33]
	v_lshl_add_u64 v[36:37], s[52:53], 0, v[28:29]
	s_waitcnt lgkmcnt(0)
	v_mfma_f32_32x32x16_bf16 v[0:15], v[24:27], v[116:119], v[0:15]
	v_lshl_add_u64 v[38:39], s[52:53], 0, v[32:33]
	ds_read_b128 v[36:39], v212 offset:32768
	ds_read_b128 v[40:43], v212 offset:40960
	s_waitcnt vmcnt(0)
	s_waitcnt vmcnt(3)
	ds_write_b128 v206, v[144:147] offset:16384
	s_waitcnt vmcnt(2)
	ds_write_b128 v207, v[148:151] offset:16384
	s_waitcnt vmcnt(1)
	ds_write_b128 v199, v[152:155] offset:49152
	s_waitcnt vmcnt(0)
	ds_write_b128 v200, v[156:159] offset:49152
	s_waitcnt lgkmcnt(4)
	v_mfma_f32_32x32x16_bf16 v[0:15], v[40:43], v[112:115], v[0:15]
	v_or_b32_e32 v23, s0, v163
	v_or_b32_e32 v21, 3, v23
	v_cmp_lt_i32_e64 s[10:11], v21, v164
	v_or_b32_e32 v25, 18, v23
	v_cmp_lt_i32_e64 s[4:5], v23, v164
	v_cmp_lt_i32_e64 s[14:15], v25, v164
	v_or_b32_e32 v25, 19, v23
	s_nop 4
	v_exp_f32_e32 v1, v1
	v_mfma_f32_32x32x16_bf16 v[64:79], v[36:39], v[112:115], v[64:79]
	v_exp_f32_e32 v39, v2
	v_exp_f32_e32 v40, v3
	v_and_b32_e32 v36, 0xc0, v44
	v_lshlrev_b32_e32 v37, 1, v16
	v_exp_f32_e32 v0, v0
	v_exp_f32_e32 v51, v14
	v_and_or_b32 v36, v45, 24, v36
	v_and_b32_e32 v37, 32, v37
	v_and_b32_e32 v38, 0x100, v45
	v_add_f32_e32 v2, 1.0, v1
	v_exp_f32_e32 v52, v15
	v_or3_b32 v38, v36, v37, v38
	v_rcp_f32_e32 v37, v2
	v_add_f32_e32 v2, 1.0, v39
	v_add_f32_e32 v3, 1.0, v40
	v_rcp_f32_e32 v41, v2
	v_rcp_f32_e32 v42, v3
	v_add_f32_e32 v36, 1.0, v0
	v_add_f32_e32 v14, 1.0, v51
	v_rcp_f32_e32 v36, v36
	v_rcp_f32_e32 v53, v14
	v_add_f32_e32 v14, 1.0, v52
	v_or_b32_e32 v15, 2, v23
	v_exp_f32_e32 v2, v4
	v_exp_f32_e32 v3, v5
	v_rcp_f32_e32 v54, v14
	v_or_b32_e32 v14, 1, v23
	v_cmp_lt_i32_e64 s[8:9], v15, v164
	v_exp_f32_e32 v43, v6
	v_cmp_lt_i32_e64 s[6:7], v14, v164
	v_cndmask_b32_e64 v15, 1.0, v41, s[8:9]
	v_cndmask_b32_e64 v21, 1.0, v42, s[10:11]
	v_exp_f32_e32 v44, v7
	v_cndmask_b32_e64 v14, 1.0, v37, s[6:7]
	v_mul_f32_e32 v15, v21, v15
	v_cndmask_b32_e64 v20, 1.0, v36, s[4:5]
	v_mul_f32_e32 v14, v14, v15
	v_cmp_lt_i32_e64 s[16:17], v25, v164
	v_or_b32_e32 v25, 26, v23
	v_add_f32_e32 v4, 1.0, v2
	v_add_f32_e32 v5, 1.0, v3
	v_mul_f32_e32 v22, v20, v14
	v_cmp_lt_i32_e32 vcc, v25, v164
	v_or_b32_e32 v25, 27, v23
	v_rcp_f32_e32 v4, v4
	v_rcp_f32_e32 v5, v5
	v_add_f32_e32 v6, 1.0, v43
	v_exp_f32_e32 v47, v10
	v_exp_f32_e32 v48, v11
	v_cmp_lt_i32_e64 s[2:3], v25, v164
	v_mov_b32_e32 v25, v22
	v_mov_b32_e32 v29, v22
	v_rcp_f32_e32 v45, v6
	v_add_f32_e32 v7, 1.0, v44
	v_permlane32_swap_b32_e32 v25, v29
	v_cmp_gt_u32_e64 s[0:1], 32, v19
	v_rcp_f32_e32 v46, v7
	v_pk_mul_f32 v[0:1], v[0:1], v[36:37]
	v_cndmask_b32_e64 v35, v25, v29, s[0:1]
	v_mul_f32_e32 v55, v22, v35
	v_or_b32_e32 v22, 8, v23
	v_add_f32_e32 v10, 1.0, v47
	v_add_f32_e32 v11, 1.0, v48
	v_or_b32_e32 v24, 10, v23
	v_or_b32_e32 v20, 11, v23
	v_cndmask_b32_e64 v0, 0, v0, s[4:5]
	v_cmp_lt_i32_e64 s[4:5], v22, v164
	v_pk_mul_f32 v[2:3], v[2:3], v[4:5]
	v_rcp_f32_e32 v49, v10
	v_rcp_f32_e32 v50, v11
	v_exp_f32_e32 v11, v13
	v_cmp_lt_i32_e64 s[12:13], v20, v164
	v_cndmask_b32_e64 v22, 1.0, v4, s[4:5]
	v_cndmask_b32_e64 v2, 0, v2, s[4:5]
	v_mul_f32_e32 v4, v43, v45
	v_cmp_lt_i32_e64 s[4:5], v24, v164
	v_exp_f32_e32 v10, v12
	v_cndmask_b32_e64 v20, 1.0, v46, s[12:13]
; __device__ __forceinline__ int crow(int r, int hi) { return (r & 3) + 8 * (r >> 2) + 4 * hi; }
; __device__ __forceinline__ void sb_half(f32x16& p, float& carry, bool masked, int krow0, int tq, int hi) {
;     ...
;     for (int g = 0; g < 4; ++g) {
;         float q[4];
; #pragma unroll
;         for (int i = 0; i < 4; ++i) { const int r = 4 * g + i; const float e = __builtin_amdgcn_exp2f(p[r]); float qq = __builtin_amdgcn_rcpf(1.0f + e); float b = e * qq;
;             if (masked) { const bool keep = (krow0 + crow(r, hi)) < tq; qq = keep ? qq : 1.0f; b = keep ? b : 0.0f; }
;             q[i] = qq; p[r] = b; }
;         const float s2 = q[3] * q[2], s1 = s2 * q[1]; G[g] = s1 * q[0];
;         p[4 * g + 2] *= q[3]; p[4 * g + 1] *= s2; p[4 * g] *= s1;
;     }
;     float run = carry;
; #pragma unroll
;     for (int g = 3; g >= 0; --g) { const unsigned gu = __builtin_bit_cast(unsigned, G[g]); auto sw = __builtin_amdgcn_permlane32_swap(gu, gu, false, false);
;         const float partner = __builtin_bit_cast(float, hi ? sw[0] : sw[1]);
;         const float base = hi ? run : run * partner;
;         p[4 * g] *= base; p[4 * g + 1] *= base; p[4 * g + 2] *= base; p[4 * g + 3] *= base; run *= G[g] * partner; }
;     carry = run;
; __device__ __forceinline__ void sb_unit(const bf16* __restrict__ Qb, const bf16* __restrict__ Kh, const bf16* __restrict__ Vh, bf16* __restrict__ Ob, int q0, char* lds, const int wv0) {
;     ...
;     const int NT = (q0 + 256) / KVBLK;
;     f32x16 o[4] = {}; bf16x8 qr[8];
;     const int tq = q0 + wid * 32 + r32;
;     const bf16* Qw = Qb + (size_t)tq * LD + hi * 8;
; #pragma unroll
;     for (int d0 = 0; d0 < 8; ++d0) qr[d0] = *reinterpret_cast<const bf16x8*>(Qw + d0 * 16);
;     const int sr = tid >> 4, sc = (tid & 15) * 8, vst0 = v_st(sr, sc), vst1 = v_st(32 + sr, sc);
;     const int vb0 = (int)(uintptr_t)V_lds + v_rd_base(lane);
;     struct { bf16x8 vs0, vs1, ks0, ks1; } sr_[1];
;     ...
;     f32x16 pA0, pA1, pB0, pB1; bf16x8 pa0, pa1, pa2, pa3; float carry = 1.0f;
;     constexpr int SE = 0, SO = 0;
;     __syncthreads();
;     SLOAD(SE, K0(0)); asm volatile("s_waitcnt vmcnt(0)" ::: "memory"); SWRITE(0, SE); __syncthreads();
;     qkt(pA0, pA1, K_lds, qr, r32, hi); sb_half(pA1, carry, true, K0(0) + 32, tq, hi);
;     SLOAD(SO, K0(1));
;     SWAIT(); SWRITE(1, SO); __syncthreads();
;     volatile unsigned* votes = (volatile unsigned*)(lds + 4 * SHM_V);
	v_cndmask_b32_e64 v4, 0, v4, s[4:5]
	v_cndmask_b32_e64 v1, 0, v1, s[6:7]
	v_mul_f32_e32 v24, v20, v4
	v_mul_f32_e32 v4, v44, v46
	v_pk_mul_f32 v[0:1], v[0:1], v[14:15]
	v_mul_f32_e32 v14, v39, v41
	v_cndmask_b32_e64 v25, 0, v4, s[12:13]
	v_or_b32_e32 v4, 17, v23
	v_add_f32_e32 v13, 1.0, v11
	v_cndmask_b32_e64 v14, 0, v14, s[8:9]
	v_cmp_lt_i32_e64 s[8:9], v4, v164
	v_mul_f32_e32 v4, v47, v49
	v_add_f32_e32 v12, 1.0, v10
	v_rcp_f32_e32 v13, v13
	v_cndmask_b32_e64 v26, 1.0, v49, s[14:15]
	v_cndmask_b32_e64 v27, 1.0, v50, s[16:17]
	v_mul_f32_e32 v14, v21, v14
	v_or_b32_e32 v21, 9, v23
	v_cndmask_b32_e64 v4, 0, v4, s[14:15]
	v_exp_f32_e32 v7, v9
	v_rcp_f32_e32 v12, v12
	v_cmp_lt_i32_e64 s[6:7], v21, v164
	v_mul_f32_e32 v21, v27, v26
	v_mul_f32_e32 v26, v27, v4
	v_mul_f32_e32 v4, v48, v50
	v_exp_f32_e32 v6, v8
	v_cndmask_b32_e64 v27, 0, v4, s[16:17]
	v_or_b32_e32 v4, 25, v23
	v_cndmask_b32_e32 v28, 1.0, v53, vcc
	v_cndmask_b32_e64 v34, 1.0, v54, s[2:3]
	v_mul_f32_e32 v15, v40, v42
	v_or_b32_e32 v29, 16, v23
	v_or_b32_e32 v23, 24, v23
	v_cmp_lt_i32_e64 s[14:15], v4, v164
	v_cndmask_b32_e64 v15, 0, v15, s[10:11]
	v_cmp_lt_i32_e64 s[10:11], v29, v164
	v_cmp_lt_i32_e64 s[12:13], v23, v164
	v_cndmask_b32_e64 v4, 1.0, v13, s[14:15]
	v_mul_f32_e32 v29, v34, v28
	v_add_f32_e32 v9, 1.0, v7
	v_cndmask_b32_e64 v23, 1.0, v12, s[12:13]
	v_mul_f32_e32 v28, v4, v29
	v_add_f32_e32 v8, 1.0, v6
	v_rcp_f32_e32 v9, v9
	v_mul_f32_e32 v4, v23, v28
	v_rcp_f32_e32 v8, v8
	v_mov_b32_e32 v23, v4
	v_mov_b32_e32 v30, v4
	s_nop 1
	v_permlane32_swap_b32_e32 v23, v30
	v_cndmask_b32_e64 v36, v23, v30, s[0:1]
	v_mul_f32_e32 v31, v4, v36
	v_cndmask_b32_e64 v32, 1.0, v5, s[6:7]
	v_cndmask_b32_e64 v5, 1.0, v9, s[8:9]
	v_cndmask_b32_e64 v4, 1.0, v45, s[4:5]
	v_cndmask_b32_e64 v33, 1.0, v8, s[10:11]
	v_pk_mul_f32 v[4:5], v[4:5], v[20:21]
	v_pk_mul_f32 v[6:7], v[6:7], v[8:9]
	v_pk_mul_f32 v[8:9], v[32:33], v[4:5]
	v_cndmask_b32_e64 v7, 0, v7, s[8:9]
	v_mov_b32_e32 v20, v9
	v_mov_b32_e32 v23, v9
	s_nop 1
	v_permlane32_swap_b32_e32 v20, v23
	v_cndmask_b32_e64 v23, v20, v23, s[0:1]
	v_pk_mul_f32 v[32:33], v[22:23], v[8:9]
	v_cndmask_b32_e64 v6, 0, v6, s[10:11]
	v_mov_b32_e32 v9, v32
	v_mov_b32_e32 v20, v32
	s_nop 1
	v_permlane32_swap_b32_e32 v9, v20
	v_cndmask_b32_e64 v30, v9, v20, s[0:1]
	v_mov_b32_e32 v20, v5
	v_mov_b32_e32 v9, v4
	v_pk_mul_f32 v[4:5], v[6:7], v[20:21]
	v_pk_mul_f32 v[6:7], v[32:33], v[30:31]
	v_cndmask_b32_e64 v3, 0, v3, s[6:7]
	v_mul_f32_e32 v6, v6, v7
	v_pk_mul_f32 v[2:3], v[2:3], v[8:9]
	v_mul_f32_e32 v8, v6, v35
	v_mul_f32_e32 v215, v55, v6
	v_cndmask_b32_e64 v6, v6, v8, s[0:1]
	v_pk_mul_f32 v[186:187], v[0:1], v[6:7] op_sel_hi:[1,0]
	v_mul_f32_e32 v0, v7, v30
	v_cndmask_b32_e64 v0, v7, v0, s[0:1]
	v_pk_mul_f32 v[188:189], v[2:3], v[0:1] op_sel_hi:[1,0]
	v_pk_mul_f32 v[180:181], v[24:25], v[0:1] op_sel_hi:[1,0]
	v_mul_f32_e32 v0, v31, v23
	v_pk_mul_f32 v[2:3], v[10:11], v[12:13]
	v_cndmask_b32_e64 v0, v31, v0, s[0:1]
	v_cndmask_b32_e64 v3, 0, v3, s[14:15]
	v_cndmask_b32_e64 v2, 0, v2, s[12:13]
	v_pk_mul_f32 v[190:191], v[4:5], v[0:1] op_sel_hi:[1,0]
	v_pk_mul_f32 v[182:183], v[26:27], v[0:1] op_sel_hi:[1,0]
	v_cndmask_b32_e64 v0, 1.0, v36, s[0:1]
	v_pk_mul_f32 v[2:3], v[2:3], v[28:29]
	s_add_i32 s4, s95, 0x60
	v_pk_mul_f32 v[192:193], v[0:1], v[2:3] op_sel_hi:[0,1]
	v_mul_f32_e32 v1, v51, v53
	v_cndmask_b32_e32 v1, 0, v1, vcc
	v_mul_f32_e32 v2, v34, v1
	v_mul_f32_e32 v1, v52, v54
	v_cndmask_b32_e64 v3, 0, v1, s[2:3]
	v_pk_mul_f32 v[184:185], v[0:1], v[2:3] op_sel_hi:[0,1]
	v_and_b32_e32 v0, 15, v16
	v_lshlrev_b32_e32 v160, 4, v0
	v_add_u32_e32 v0, s4, v17
	v_ashrrev_i32_e32 v1, 31, v0
	v_lshlrev_b64 v[0:1], 11, v[0:1]
	v_lshl_add_u64 v[170:171], s[58:59], 0, v[0:1]
	v_add3_u32 v0, s95, 64, v17
	v_ashrrev_i32_e32 v1, 31, v0
	v_lshlrev_b64 v[0:1], 11, v[0:1]
	v_lshl_add_u64 v[172:173], s[58:59], 0, v[0:1]
	v_add3_u32 v0, s95, 32, v17
	v_ashrrev_i32_e32 v1, 31, v0
	v_lshlrev_b64 v[0:1], 11, v[0:1]
	v_lshl_add_u64 v[174:175], s[58:59], 0, v[0:1]
	v_add_u32_e32 v0, s95, v17
	v_ashrrev_i32_e32 v1, 31, v0
	v_lshlrev_b64 v[0:1], 11, v[0:1]
	v_add_u32_e32 v198, s18, v38
	s_addk_i32 s18, 0x4000
	v_lshl_add_u64 v[176:177], s[58:59], 0, v[0:1]
	v_mov_b32_e32 v0, 0
	v_pk_mul_f32 v[178:179], v[14:15], v[6:7] op_sel_hi:[1,0]
	v_cmp_eq_u32_e64 s[2:3], 0, v19
	v_add_u32_e32 v165, s18, v38
	v_mov_b32_e32 v1, v0
	v_mov_b32_e32 v2, v0
	v_mov_b32_e32 v3, v0
	v_mov_b32_e32 v4, v0
	v_mov_b32_e32 v5, v0
	v_mov_b32_e32 v6, v0
	v_mov_b32_e32 v7, v0
	v_mov_b32_e32 v8, v0
	v_mov_b32_e32 v9, v0
	v_mov_b32_e32 v10, v0
	v_mov_b32_e32 v11, v0
	v_mov_b32_e32 v12, v0
	v_mov_b32_e32 v13, v0
	v_mov_b32_e32 v14, v0
	v_mov_b32_e32 v15, v0
	v_mov_b32_e32 v16, v0
	v_mov_b32_e32 v17, v0
	v_mov_b32_e32 v18, v0
	v_mov_b32_e32 v19, v0
	v_mov_b32_e32 v20, v0
	v_mov_b32_e32 v21, v0
	v_mov_b32_e32 v22, v0
	v_mov_b32_e32 v23, v0
	v_mov_b32_e32 v24, v0
	v_mov_b32_e32 v25, v0
	v_mov_b32_e32 v26, v0
	v_mov_b32_e32 v27, v0
	v_mov_b32_e32 v28, v0
	v_mov_b32_e32 v29, v0
	v_mov_b32_e32 v30, v0
	v_mov_b32_e32 v31, v0
	v_mov_b32_e32 v32, v0
	v_mov_b32_e32 v33, v0
	v_mov_b32_e32 v34, v0
	v_mov_b32_e32 v35, v0
	v_mov_b32_e32 v36, v0
	v_mov_b32_e32 v37, v0
	v_mov_b32_e32 v38, v0
	v_mov_b32_e32 v39, v0
	v_mov_b32_e32 v40, v0
	v_mov_b32_e32 v41, v0
	v_mov_b32_e32 v42, v0
	v_mov_b32_e32 v43, v0
	v_mov_b32_e32 v44, v0
	v_mov_b32_e32 v45, v0
	v_mov_b32_e32 v46, v0
	v_mov_b32_e32 v47, v0
	v_mov_b32_e32 v48, v0
	v_mov_b32_e32 v49, v0
	v_mov_b32_e32 v50, v0
	v_mov_b32_e32 v51, v0
	v_mov_b32_e32 v52, v0
	v_mov_b32_e32 v53, v0
	v_mov_b32_e32 v54, v0
	v_mov_b32_e32 v55, v0
	v_mov_b32_e32 v56, v0
	v_mov_b32_e32 v57, v0
	v_mov_b32_e32 v58, v0
	v_mov_b32_e32 v59, v0
	v_mov_b32_e32 v60, v0
	v_mov_b32_e32 v61, v0
	v_mov_b32_e32 v62, v0
	v_mov_b32_e32 v63, v0
	s_waitcnt lgkmcnt(0)
	s_barrier
	s_branch .LBB0_287

; #define TID() (wv0 * 64 + (int)__builtin_amdgcn_mbcnt_hi(~0u, __builtin_amdgcn_mbcnt_lo(~0u, 0u)))
; __device__ __forceinline__ int opaque(int x) { asm volatile("" : "+v"(x)); return x; }
; __device__ __forceinline__ int v_st(int k, int c) { const int kk = (k & ~0xC) | ((k & 4) << 1) | ((k & 8) >> 1); return ((kk >> 3) * 4 + (c >> 5)) * 512 + ((kk & 7) * 32 + (c & 31)) * 2; }
; __device__ __forceinline__ int v_rd_base(int lane) { return ((lane & 3) << 3) | (((lane >> 2) & 3) << 6) | (((lane >> 4) & 1) << 5) | (((lane >> 5) & 1) << 8); }
; #define SLOAD(i, k0) do { sr_[i].vs0 = *reinterpret_cast<const bf16x8*>(&Vh[(size_t)((k0) + sr) * LD + sc]); sr_[i].vs1 = *reinterpret_cast<const bf16x8*>(&Vh[(size_t)((k0) + 32 + sr) * LD + sc]); \
;     sr_[i].ks0 = *reinterpret_cast<const bf16x8*>(&Kh[(size_t)((k0) + sr) * LD + sc]); sr_[i].ks1 = *reinterpret_cast<const bf16x8*>(&Kh[(size_t)((k0) + 32 + sr) * LD + sc]); } while (0)
; #define SWAIT() asm volatile("s_waitcnt vmcnt(0)" ::: "memory")
; __device__ __forceinline__ void sb_unit(const bf16* __restrict__ Qb, const bf16* __restrict__ Kh, const bf16* __restrict__ Vh, bf16* __restrict__ Ob, int q0, char* lds, const int wv0) {
;     const int tid = opaque(TID()), wid = tid >> 6, lane = tid & 63, r32 = lane & 31, hi = lane >> 5;
;     char* V_lds = lds; char* K_lds = lds + 2 * SHM_V;
;     const int NT = (q0 + 256) / KVBLK;
;     f32x16 o[4] = {}; bf16x8 qr[8];
;     const int tq = q0 + wid * 32 + r32;
;     const bf16* Qw = Qb + (size_t)tq * LD + hi * 8;
; #pragma unroll
;     for (int d0 = 0; d0 < 8; ++d0) qr[d0] = *reinterpret_cast<const bf16x8*>(Qw + d0 * 16);
;     const int sr = tid >> 4, sc = (tid & 15) * 8, vst0 = v_st(sr, sc), vst1 = v_st(32 + sr, sc);
;     const int vb0 = (int)(uintptr_t)V_lds + v_rd_base(lane);
;     struct { bf16x8 vs0, vs1, ks0, ks1; } sr_[1];
;     ...
;     f32x16 pA0, pA1, pB0, pB1; bf16x8 pa0, pa1, pa2, pa3; float carry = 1.0f;
;     constexpr int SE = 0, SO = 0;
;     __syncthreads();
;     SLOAD(SE, K0(0)); asm volatile("s_waitcnt vmcnt(0)" ::: "memory"); SWRITE(0, SE); __syncthreads();
;     qkt(pA0, pA1, K_lds, qr, r32, hi); sb_half(pA1, carry, true, K0(0) + 32, tq, hi);
;     SLOAD(SO, K0(1));
;     SWAIT(); SWRITE(1, SO); __syncthreads();
.LBB0_1225:
	s_xor_b64 s[60:61], s[0:1], -1
	s_and_b64 s[0:1], s[0:1], exec
	v_mov_b32_e32 v16, v204
	s_cselect_b32 s94, s93, s92
	s_add_i32 s1, s94, 0x100
	v_ashrrev_i32_e32 v18, 6, v16
	v_and_b32_e32 v253, 31, v16
	v_lshl_add_u32 v162, v18, 5, s94
	v_or_b32_e32 v164, v162, v253
	v_ashrrev_i32_e32 v165, 31, v164
	v_bfe_u32 v252, v16, 5, 1
	v_lshlrev_b64 v[0:1], 11, v[164:165]
	v_lshl_add_u64 v[0:1], s[50:51], 0, v[0:1]
	v_lshlrev_b32_e32 v160, 4, v252
	s_lshr_b32 s40, s1, 6
	v_lshl_add_u64 v[0:1], v[0:1], 0, v[160:161]
	v_lshlrev_b32_e32 v19, 3, v16
	s_cmp_lg_u32 0, -1
	global_load_dwordx4 v[140:143], v[0:1], off
	global_load_dwordx4 v[136:139], v[0:1], off offset:32
	global_load_dwordx4 v[132:135], v[0:1], off offset:64
	global_load_dwordx4 v[128:131], v[0:1], off offset:96
	global_load_dwordx4 v[124:127], v[0:1], off offset:128
	global_load_dwordx4 v[120:123], v[0:1], off offset:160
	global_load_dwordx4 v[116:119], v[0:1], off offset:192
	global_load_dwordx4 v[112:115], v[0:1], off offset:224
	v_ashrrev_i32_e32 v17, 4, v16
	v_and_b32_e32 v0, 0x78, v19
	s_cselect_b32 s18, 0, 0
	s_add_i32 s0, s94, 0xc0
	v_lshlrev_b32_e32 v30, 1, v0
	v_add_u32_e32 v0, s0, v17
	v_ashrrev_i32_e32 v1, 31, v0
	s_add_i32 s0, s94, 0xe0
	v_lshlrev_b64 v[8:9], 11, v[0:1]
	v_add_u32_e32 v0, s0, v17
	v_ashrrev_i32_e32 v1, 31, v0
	v_lshlrev_b64 v[12:13], 11, v[0:1]
	v_or_b32_e32 v8, v8, v30
	v_or_b32_e32 v12, v12, v30
	v_lshl_add_u64 v[10:11], s[54:55], 0, v[8:9]
	v_lshl_add_u64 v[14:15], s[54:55], 0, v[12:13]
	v_lshl_add_u64 v[20:21], s[52:53], 0, v[8:9]
	s_waitcnt vmcnt(63) expcnt(7) lgkmcnt(15)
	s_barrier
	global_load_dwordx4 v[0:3], v[10:11], off
	global_load_dwordx4 v[4:7], v[14:15], off
	v_lshl_add_u64 v[22:23], s[52:53], 0, v[12:13]
	global_load_dwordx4 v[8:11], v[20:21], off
	global_load_dwordx4 v[12:15], v[22:23], off
	v_and_b32_e32 v21, 0xfffff0, v17
	v_lshlrev_b32_e32 v22, 1, v17
	v_lshrrev_b32_e32 v23, 1, v17
	v_and_b32_e32 v24, 3, v17
	v_add_u32_e32 v25, 32, v17
	v_and_or_b32 v21, v22, 8, v21
	v_and_or_b32 v22, v23, 4, v24
	v_and_b32_e32 v23, 0xfffff0, v25
	v_lshlrev_b32_e32 v24, 1, v25
	v_and_b32_e32 v20, 0x70, v16
	v_bfe_u32 v19, v19, 5, 2
	v_lshlrev_b32_e32 v26, 8, v17
	v_lshlrev_b32_e32 v25, 8, v25
	v_lshrrev_b32_e32 v21, 1, v21
	v_and_or_b32 v23, v24, 8, v23
	v_bitop3_b32 v24, v30, v26, v20 bitop3:0xde
	v_bitop3_b32 v20, v30, v25, v20 bitop3:0xde
	v_or_b32_e32 v21, v21, v19
	v_lshrrev_b32_e32 v23, 1, v23
	v_lshlrev_b32_e32 v22, 6, v22
	v_and_b32_e32 v27, 48, v30
	v_add_u32_e32 v200, 0, v20
	v_lshlrev_b32_e32 v20, 9, v21
	v_or_b32_e32 v19, v23, v19
	v_lshlrev_b32_e32 v44, 4, v16
	v_or3_b32 v20, v20, v22, v27
	v_lshlrev_b32_e32 v19, 9, v19
	v_lshlrev_b32_e32 v29, 8, v253
	v_and_b32_e32 v31, 0x70, v44
	v_or3_b32 v19, v19, v22, v27
	v_add_u32_e32 v206, 0, v20
	v_add_u32_e32 v199, 0, v24
	v_add_u32_e32 v207, 0, v19
	s_mov_b32 s2, 0xfffd0000
	s_mov_b32 s3, -1
	v_add_u32_e32 v146, s1, v17
	v_ashrrev_i32_e32 v147, 31, v146
	v_lshlrev_b64 v[146:147], 11, v[146:147]
	v_or_b32_e32 v146, v146, v30
	v_lshl_add_u64 v[150:151], v[146:147], 0, s[2:3]
	v_lshl_add_u64 v[146:147], v[146:147], 0, s[48:49]
	v_lshl_add_u64 v[144:145], s[54:55], 0, v[146:147]
	v_lshl_add_u64 v[152:153], s[52:53], 0, v[146:147]
	v_lshl_add_u64 v[148:149], s[54:55], 0, v[150:151]
	v_lshl_add_u64 v[156:157], s[52:53], 0, v[150:151]
	global_load_dwordx4 v[144:147], v[144:145], off
	global_load_dwordx4 v[148:151], v[148:149], off
	global_load_dwordx4 v[152:155], v[152:153], off
	global_load_dwordx4 v[156:159], v[156:157], off
	s_waitcnt vmcnt(4)
	v_or_b32_e32 v19, 64, v160
	v_bitop3_b32 v19, v19, v29, v31 bitop3:0xde
	v_add_u32_e32 v208, 0, v19
	v_or_b32_e32 v19, 0x60, v160
	v_bitop3_b32 v19, v19, v29, v31 bitop3:0xde
	v_add_u32_e32 v209, 0, v19
	v_or_b32_e32 v19, 0x80, v160
	v_bitop3_b32 v19, v19, v29, v31 bitop3:0xde
	v_add_u32_e32 v210, 0, v19
	v_or_b32_e32 v19, 0xa0, v160
	v_bitop3_b32 v19, v19, v29, v31 bitop3:0xde
	v_add_u32_e32 v211, 0, v19
	v_or_b32_e32 v19, 0xc0, v160
	v_bitop3_b32 v19, v19, v29, v31 bitop3:0xde
	v_add_u32_e32 v203, 0, v19
	v_or_b32_e32 v19, 0xe0, v160
	v_add_u32_e32 v28, s1, v17
	v_bitop3_b32 v19, v19, v29, v31 bitop3:0xde
	s_mov_b32 s2, 0xfffd0000
	s_mov_b32 s3, -1
	s_waitcnt vmcnt(7)
	ds_write_b128 v206, v[0:3]
	s_waitcnt vmcnt(6)
	ds_write_b128 v207, v[4:7]
	s_waitcnt vmcnt(5)
	ds_write_b128 v199, v[8:11] offset:32768
	s_waitcnt vmcnt(4)
	ds_write_b128 v200, v[12:15] offset:32768
	v_bitop3_b32 v0, v160, v29, v31 bitop3:0xde
	v_add_u32_e32 v201, 0, v0
	s_waitcnt lgkmcnt(0)
	s_barrier
; __device__ __forceinline__ int crow(int r, int hi) { return (r & 3) + 8 * (r >> 2) + 4 * hi; }
; #define SLOAD(i, k0) do { sr_[i].vs0 = *reinterpret_cast<const bf16x8*>(&Vh[(size_t)((k0) + sr) * LD + sc]); sr_[i].vs1 = *reinterpret_cast<const bf16x8*>(&Vh[(size_t)((k0) + 32 + sr) * LD + sc]); \
;     sr_[i].ks0 = *reinterpret_cast<const bf16x8*>(&Kh[(size_t)((k0) + sr) * LD + sc]); sr_[i].ks1 = *reinterpret_cast<const bf16x8*>(&Kh[(size_t)((k0) + 32 + sr) * LD + sc]); } while (0)
; #define SWRITE(b, i) do { *(bf16x8*)(V_lds + (b) * SHM_V + vst0) = sr_[i].vs0; *(bf16x8*)(V_lds + (b) * SHM_V + vst1) = sr_[i].vs1; const int kc = sc * 2; \
;     *(bf16x8*)(K_lds + (b) * SHM_K + KSWZ(sr, kc)) = sr_[i].ks0; *(bf16x8*)(K_lds + (b) * SHM_K + KSWZ(32 + sr, kc)) = sr_[i].ks1; } while (0)
; #define SWAIT() asm volatile("s_waitcnt vmcnt(0)" ::: "memory")
; __device__ __forceinline__ void qkt(f32x16& p0, f32x16& p1, const char* Ks, const bf16x8* qr, int r32, int hi) {
;     p0 = f32x16{}; p1 = f32x16{};
; #pragma unroll
;     for (int d0 = 0; d0 < 8; ++d0) { const int cb = (d0 * 16 + hi * 8) * 2;
;         const bf16x8 b0 = *reinterpret_cast<const bf16x8*>(Ks + KSWZ(r32, cb));
;         const bf16x8 b1 = *reinterpret_cast<const bf16x8*>(Ks + KSWZ(32 + r32, cb));
;         p0 = __builtin_amdgcn_mfma_f32_32x32x16_bf16(b0, qr[d0], p0, 0, 0, 0);
;         p1 = __builtin_amdgcn_mfma_f32_32x32x16_bf16(b1, qr[d0], p1, 0, 0, 0); }
; }
; __device__ __forceinline__ void sb_half(f32x16& p, float& carry, bool masked, int krow0, int tq, int hi) {
;     ...
;         for (int i = 0; i < 4; ++i) { const int r = 4 * g + i; const float e = __builtin_amdgcn_exp2f(p[r]); float qq = __builtin_amdgcn_rcpf(1.0f + e); float b = e * qq;
;             if (masked) { const bool keep = (krow0 + crow(r, hi)) < tq; qq = keep ? qq : 1.0f; b = keep ? b : 0.0f; }
;             q[i] = qq; p[r] = b; }
;         const float s2 = q[3] * q[2], s1 = s2 * q[1]; G[g] = s1 * q[0];
;         p[4 * g + 2] *= q[3]; p[4 * g + 1] *= s2; p[4 * g] *= s1;
; __device__ __forceinline__ void sb_unit(const bf16* __restrict__ Qb, const bf16* __restrict__ Kh, const bf16* __restrict__ Vh, bf16* __restrict__ Ob, int q0, char* lds, const int wv0) {
;     ...
;     qkt(pA0, pA1, K_lds, qr, r32, hi); sb_half(pA1, carry, true, K0(0) + 32, tq, hi);
;     SLOAD(SO, K0(1));
;     SWAIT(); SWRITE(1, SO); __syncthreads();
	ds_read_b128 v[0:3], v201 offset:32768
	ds_read_b128 v[4:7], v201 offset:40960
	s_waitcnt lgkmcnt(1)
	v_mfma_f32_32x32x16_bf16 v[64:79], v[0:3], v[140:143], 0
	v_or_b32_e32 v0, 32, v160
	v_bitop3_b32 v0, v0, v29, v31 bitop3:0xde
	v_add_u32_e32 v202, 0, v0
	ds_read_b128 v[20:23], v202 offset:32768
	ds_read_b128 v[24:27], v202 offset:40960
	v_ashrrev_i32_e32 v29, 31, v28
	v_add_u32_e32 v212, 0, v19
	v_and_b32_e32 v19, 63, v16
	s_waitcnt lgkmcnt(2)
	v_mfma_f32_32x32x16_bf16 v[0:15], v[4:7], v[140:143], 0
	v_lshlrev_b32_e32 v45, 3, v19
	v_lshlrev_b32_e32 v163, 2, v252
	s_add_i32 s41, 0, 0x10000
	v_lshl_add_u32 v166, v18, 2, s41
	s_mov_b32 s79, 2
	v_mov_b32_e32 v167, s47
	v_add_u32_e32 v168, 32, v166
	s_waitcnt lgkmcnt(1)
	v_mfma_f32_32x32x16_bf16 v[64:79], v[20:23], v[136:139], v[64:79]
	v_mov_b32_e32 v169, s47
	s_mov_b64 s[62:63], 0
	v_mov_b32_e32 v213, v163
	s_waitcnt lgkmcnt(0)
	v_mfma_f32_32x32x16_bf16 v[0:15], v[24:27], v[136:139], v[0:15]
	ds_read_b128 v[20:23], v208 offset:32768
	ds_read_b128 v[24:27], v208 offset:40960
	s_waitcnt lgkmcnt(1)
	v_mfma_f32_32x32x16_bf16 v[64:79], v[20:23], v[132:135], v[64:79]
	s_waitcnt lgkmcnt(0)
	v_mfma_f32_32x32x16_bf16 v[0:15], v[24:27], v[132:135], v[0:15]
	ds_read_b128 v[20:23], v209 offset:32768
	ds_read_b128 v[24:27], v209 offset:40960
	s_waitcnt lgkmcnt(1)
	v_mfma_f32_32x32x16_bf16 v[64:79], v[20:23], v[128:131], v[64:79]
	s_waitcnt lgkmcnt(0)
	v_mfma_f32_32x32x16_bf16 v[0:15], v[24:27], v[128:131], v[0:15]
	ds_read_b128 v[20:23], v210 offset:32768
	ds_read_b128 v[24:27], v210 offset:40960
	s_waitcnt lgkmcnt(1)
	v_mfma_f32_32x32x16_bf16 v[64:79], v[20:23], v[124:127], v[64:79]
	s_waitcnt lgkmcnt(0)
	v_mfma_f32_32x32x16_bf16 v[0:15], v[24:27], v[124:127], v[0:15]
	ds_read_b128 v[20:23], v211 offset:32768
	ds_read_b128 v[24:27], v211 offset:40960
	s_waitcnt lgkmcnt(1)
	v_mfma_f32_32x32x16_bf16 v[64:79], v[20:23], v[120:123], v[64:79]
	ds_read_b128 v[20:23], v203 offset:32768
	s_waitcnt lgkmcnt(1)
	v_mfma_f32_32x32x16_bf16 v[0:15], v[24:27], v[120:123], v[0:15]
	ds_read_b128 v[24:27], v203 offset:40960
	s_waitcnt lgkmcnt(1)
	v_mfma_f32_32x32x16_bf16 v[64:79], v[20:23], v[116:119], v[64:79]
	v_lshlrev_b64 v[20:21], 11, v[28:29]
	v_or_b32_e32 v20, v20, v30
	v_lshl_add_u64 v[28:29], v[20:21], 0, s[48:49]
	v_lshl_add_u64 v[32:33], v[20:21], 0, s[2:3]
	v_lshl_add_u64 v[30:31], s[54:55], 0, v[28:29]
	v_lshl_add_u64 v[34:35], s[54:55], 0, v[32:33]
	v_lshl_add_u64 v[36:37], s[52:53], 0, v[28:29]
	s_waitcnt lgkmcnt(0)
	v_mfma_f32_32x32x16_bf16 v[0:15], v[24:27], v[116:119], v[0:15]
	v_lshl_add_u64 v[38:39], s[52:53], 0, v[32:33]
	ds_read_b128 v[36:39], v212 offset:32768
	ds_read_b128 v[40:43], v212 offset:40960
	s_waitcnt vmcnt(0)
	s_waitcnt vmcnt(3)
	ds_write_b128 v206, v[144:147] offset:16384
	s_waitcnt vmcnt(2)
	ds_write_b128 v207, v[148:151] offset:16384
	s_waitcnt vmcnt(1)
	ds_write_b128 v199, v[152:155] offset:49152
	s_waitcnt vmcnt(0)
	ds_write_b128 v200, v[156:159] offset:49152
	s_waitcnt lgkmcnt(4)
	v_mfma_f32_32x32x16_bf16 v[0:15], v[40:43], v[112:115], v[0:15]
	v_or_b32_e32 v23, s0, v163
	v_or_b32_e32 v21, 3, v23
	v_cmp_lt_i32_e64 s[10:11], v21, v164
	v_or_b32_e32 v25, 18, v23
	v_cmp_lt_i32_e64 s[4:5], v23, v164
	v_cmp_lt_i32_e64 s[14:15], v25, v164
	v_or_b32_e32 v25, 19, v23
	s_nop 4
	v_exp_f32_e32 v1, v1
	v_mfma_f32_32x32x16_bf16 v[64:79], v[36:39], v[112:115], v[64:79]
	v_exp_f32_e32 v39, v2
	v_exp_f32_e32 v40, v3
	v_and_b32_e32 v36, 0xc0, v44
	v_lshlrev_b32_e32 v37, 1, v16
	v_exp_f32_e32 v0, v0
	v_exp_f32_e32 v51, v14
	v_and_or_b32 v36, v45, 24, v36
	v_and_b32_e32 v37, 32, v37
	v_and_b32_e32 v38, 0x100, v45
	v_add_f32_e32 v2, 1.0, v1
	v_exp_f32_e32 v52, v15
	v_or3_b32 v38, v36, v37, v38
	v_rcp_f32_e32 v37, v2
	v_add_f32_e32 v2, 1.0, v39
	v_add_f32_e32 v3, 1.0, v40
	v_rcp_f32_e32 v41, v2
	v_rcp_f32_e32 v42, v3
	v_add_f32_e32 v36, 1.0, v0
	v_add_f32_e32 v14, 1.0, v51
	v_rcp_f32_e32 v36, v36
	v_rcp_f32_e32 v53, v14
	v_add_f32_e32 v14, 1.0, v52
	v_or_b32_e32 v15, 2, v23
	v_exp_f32_e32 v2, v4
	v_exp_f32_e32 v3, v5
	v_rcp_f32_e32 v54, v14
	v_or_b32_e32 v14, 1, v23
	v_cmp_lt_i32_e64 s[8:9], v15, v164
	v_exp_f32_e32 v43, v6
	v_cmp_lt_i32_e64 s[6:7], v14, v164
	v_cndmask_b32_e64 v15, 1.0, v41, s[8:9]
	v_cndmask_b32_e64 v21, 1.0, v42, s[10:11]
	v_exp_f32_e32 v44, v7
	v_cndmask_b32_e64 v14, 1.0, v37, s[6:7]
	v_mul_f32_e32 v15, v21, v15
	v_cndmask_b32_e64 v20, 1.0, v36, s[4:5]
	v_mul_f32_e32 v14, v14, v15
	v_cmp_lt_i32_e64 s[16:17], v25, v164
	v_or_b32_e32 v25, 26, v23
	v_add_f32_e32 v4, 1.0, v2
	v_add_f32_e32 v5, 1.0, v3
	v_mul_f32_e32 v22, v20, v14
	v_cmp_lt_i32_e32 vcc, v25, v164
	v_or_b32_e32 v25, 27, v23
	v_rcp_f32_e32 v4, v4
	v_rcp_f32_e32 v5, v5
	v_add_f32_e32 v6, 1.0, v43
	v_exp_f32_e32 v47, v10
	v_exp_f32_e32 v48, v11
	v_cmp_lt_i32_e64 s[2:3], v25, v164
	v_mov_b32_e32 v25, v22
	v_mov_b32_e32 v29, v22
	v_rcp_f32_e32 v45, v6
	v_add_f32_e32 v7, 1.0, v44
	v_permlane32_swap_b32_e32 v25, v29
	v_cmp_gt_u32_e64 s[0:1], 32, v19
	v_rcp_f32_e32 v46, v7
	v_pk_mul_f32 v[0:1], v[0:1], v[36:37]
	v_cndmask_b32_e64 v35, v25, v29, s[0:1]
	v_mul_f32_e32 v55, v22, v35
	v_or_b32_e32 v22, 8, v23
	v_add_f32_e32 v10, 1.0, v47
	v_add_f32_e32 v11, 1.0, v48
	v_or_b32_e32 v24, 10, v23
	v_or_b32_e32 v20, 11, v23
	v_cndmask_b32_e64 v0, 0, v0, s[4:5]
	v_cmp_lt_i32_e64 s[4:5], v22, v164
	v_pk_mul_f32 v[2:3], v[2:3], v[4:5]
	v_rcp_f32_e32 v49, v10
	v_rcp_f32_e32 v50, v11
	v_exp_f32_e32 v11, v13
	v_cmp_lt_i32_e64 s[12:13], v20, v164
	v_cndmask_b32_e64 v22, 1.0, v4, s[4:5]
	v_cndmask_b32_e64 v2, 0, v2, s[4:5]
	v_mul_f32_e32 v4, v43, v45
	v_cmp_lt_i32_e64 s[4:5], v24, v164
	v_exp_f32_e32 v10, v12
	v_cndmask_b32_e64 v20, 1.0, v46, s[12:13]
; __device__ __forceinline__ int crow(int r, int hi) { return (r & 3) + 8 * (r >> 2) + 4 * hi; }
; __device__ __forceinline__ int v_st(int k, int c) { const int kk = (k & ~0xC) | ((k & 4) << 1) | ((k & 8) >> 1); return ((kk >> 3) * 4 + (c >> 5)) * 512 + ((kk & 7) * 32 + (c & 31)) * 2; }
; __device__ __forceinline__ int v_rd_base(int lane) { return ((lane & 3) << 3) | (((lane >> 2) & 3) << 6) | (((lane >> 4) & 1) << 5) | (((lane >> 5) & 1) << 8); }
; __device__ __forceinline__ void sb_half(f32x16& p, float& carry, bool masked, int krow0, int tq, int hi) {
;     float G[4];
; #pragma unroll
;     for (int g = 0; g < 4; ++g) {
;         float q[4];
; #pragma unroll
;         for (int i = 0; i < 4; ++i) { const int r = 4 * g + i; const float e = __builtin_amdgcn_exp2f(p[r]); float qq = __builtin_amdgcn_rcpf(1.0f + e); float b = e * qq;
;             if (masked) { const bool keep = (krow0 + crow(r, hi)) < tq; qq = keep ? qq : 1.0f; b = keep ? b : 0.0f; }
;             q[i] = qq; p[r] = b; }
;         const float s2 = q[3] * q[2], s1 = s2 * q[1]; G[g] = s1 * q[0];
;         p[4 * g + 2] *= q[3]; p[4 * g + 1] *= s2; p[4 * g] *= s1;
;     }
;     float run = carry;
; #pragma unroll
;     for (int g = 3; g >= 0; --g) { const unsigned gu = __builtin_bit_cast(unsigned, G[g]); auto sw = __builtin_amdgcn_permlane32_swap(gu, gu, false, false);
;         const float partner = __builtin_bit_cast(float, hi ? sw[0] : sw[1]);
;         const float base = hi ? run : run * partner;
;         p[4 * g] *= base; p[4 * g + 1] *= base; p[4 * g + 2] *= base; p[4 * g + 3] *= base; run *= G[g] * partner; }
;     carry = run;
; }
; __device__ __forceinline__ void sb_unit(const bf16* __restrict__ Qb, const bf16* __restrict__ Kh, const bf16* __restrict__ Vh, bf16* __restrict__ Ob, int q0, char* lds, const int wv0) {
;     ...
;     f32x16 o[4] = {}; bf16x8 qr[8];
;     ...
;     const int sr = tid >> 4, sc = (tid & 15) * 8, vst0 = v_st(sr, sc), vst1 = v_st(32 + sr, sc);
;     const int vb0 = (int)(uintptr_t)V_lds + v_rd_base(lane);
	v_cndmask_b32_e64 v4, 0, v4, s[4:5]
	v_cndmask_b32_e64 v1, 0, v1, s[6:7]
	v_mul_f32_e32 v24, v20, v4
	v_mul_f32_e32 v4, v44, v46
	v_pk_mul_f32 v[0:1], v[0:1], v[14:15]
	v_mul_f32_e32 v14, v39, v41
	v_cndmask_b32_e64 v25, 0, v4, s[12:13]
	v_or_b32_e32 v4, 17, v23
	v_add_f32_e32 v13, 1.0, v11
	v_cndmask_b32_e64 v14, 0, v14, s[8:9]
	v_cmp_lt_i32_e64 s[8:9], v4, v164
	v_mul_f32_e32 v4, v47, v49
	v_add_f32_e32 v12, 1.0, v10
	v_rcp_f32_e32 v13, v13
	v_cndmask_b32_e64 v26, 1.0, v49, s[14:15]
	v_cndmask_b32_e64 v27, 1.0, v50, s[16:17]
	v_mul_f32_e32 v14, v21, v14
	v_or_b32_e32 v21, 9, v23
	v_cndmask_b32_e64 v4, 0, v4, s[14:15]
	v_exp_f32_e32 v7, v9
	v_rcp_f32_e32 v12, v12
	v_cmp_lt_i32_e64 s[6:7], v21, v164
	v_mul_f32_e32 v21, v27, v26
	v_mul_f32_e32 v26, v27, v4
	v_mul_f32_e32 v4, v48, v50
	v_exp_f32_e32 v6, v8
	v_cndmask_b32_e64 v27, 0, v4, s[16:17]
	v_or_b32_e32 v4, 25, v23
	v_cndmask_b32_e32 v28, 1.0, v53, vcc
	v_cndmask_b32_e64 v34, 1.0, v54, s[2:3]
	v_mul_f32_e32 v15, v40, v42
	v_or_b32_e32 v29, 16, v23
	v_or_b32_e32 v23, 24, v23
	v_cmp_lt_i32_e64 s[14:15], v4, v164
	v_cndmask_b32_e64 v15, 0, v15, s[10:11]
	v_cmp_lt_i32_e64 s[10:11], v29, v164
	v_cmp_lt_i32_e64 s[12:13], v23, v164
	v_cndmask_b32_e64 v4, 1.0, v13, s[14:15]
	v_mul_f32_e32 v29, v34, v28
	v_add_f32_e32 v9, 1.0, v7
	v_cndmask_b32_e64 v23, 1.0, v12, s[12:13]
	v_mul_f32_e32 v28, v4, v29
	v_add_f32_e32 v8, 1.0, v6
	v_rcp_f32_e32 v9, v9
	v_mul_f32_e32 v4, v23, v28
	v_rcp_f32_e32 v8, v8
	v_mov_b32_e32 v23, v4
	v_mov_b32_e32 v30, v4
	s_nop 1
	v_permlane32_swap_b32_e32 v23, v30
	v_cndmask_b32_e64 v36, v23, v30, s[0:1]
	v_mul_f32_e32 v31, v4, v36
	v_cndmask_b32_e64 v32, 1.0, v5, s[6:7]
	v_cndmask_b32_e64 v5, 1.0, v9, s[8:9]
	v_cndmask_b32_e64 v4, 1.0, v45, s[4:5]
	v_cndmask_b32_e64 v33, 1.0, v8, s[10:11]
	v_pk_mul_f32 v[4:5], v[4:5], v[20:21]
	v_pk_mul_f32 v[6:7], v[6:7], v[8:9]
	v_pk_mul_f32 v[8:9], v[32:33], v[4:5]
	v_cndmask_b32_e64 v7, 0, v7, s[8:9]
	v_mov_b32_e32 v20, v9
	v_mov_b32_e32 v23, v9
	s_nop 1
	v_permlane32_swap_b32_e32 v20, v23
	v_cndmask_b32_e64 v23, v20, v23, s[0:1]
	v_pk_mul_f32 v[32:33], v[22:23], v[8:9]
	v_cndmask_b32_e64 v6, 0, v6, s[10:11]
	v_mov_b32_e32 v9, v32
	v_mov_b32_e32 v20, v32
	s_nop 1
	v_permlane32_swap_b32_e32 v9, v20
	v_cndmask_b32_e64 v30, v9, v20, s[0:1]
	v_mov_b32_e32 v20, v5
	v_mov_b32_e32 v9, v4
	v_pk_mul_f32 v[4:5], v[6:7], v[20:21]
	v_pk_mul_f32 v[6:7], v[32:33], v[30:31]
	v_cndmask_b32_e64 v3, 0, v3, s[6:7]
	v_mul_f32_e32 v6, v6, v7
	v_pk_mul_f32 v[2:3], v[2:3], v[8:9]
	v_mul_f32_e32 v8, v6, v35
	v_mul_f32_e32 v215, v55, v6
	v_cndmask_b32_e64 v6, v6, v8, s[0:1]
	v_pk_mul_f32 v[186:187], v[0:1], v[6:7] op_sel_hi:[1,0]
	v_mul_f32_e32 v0, v7, v30
	v_cndmask_b32_e64 v0, v7, v0, s[0:1]
	v_pk_mul_f32 v[188:189], v[2:3], v[0:1] op_sel_hi:[1,0]
	v_pk_mul_f32 v[180:181], v[24:25], v[0:1] op_sel_hi:[1,0]
	v_mul_f32_e32 v0, v31, v23
	v_pk_mul_f32 v[2:3], v[10:11], v[12:13]
	v_cndmask_b32_e64 v0, v31, v0, s[0:1]
	v_cndmask_b32_e64 v3, 0, v3, s[14:15]
	v_cndmask_b32_e64 v2, 0, v2, s[12:13]
	v_pk_mul_f32 v[190:191], v[4:5], v[0:1] op_sel_hi:[1,0]
	v_pk_mul_f32 v[182:183], v[26:27], v[0:1] op_sel_hi:[1,0]
	v_cndmask_b32_e64 v0, 1.0, v36, s[0:1]
	v_pk_mul_f32 v[2:3], v[2:3], v[28:29]
	s_add_i32 s4, s94, 0x60
	v_pk_mul_f32 v[192:193], v[0:1], v[2:3] op_sel_hi:[0,1]
	v_mul_f32_e32 v1, v51, v53
	v_cndmask_b32_e32 v1, 0, v1, vcc
	v_mul_f32_e32 v2, v34, v1
	v_mul_f32_e32 v1, v52, v54
	v_cndmask_b32_e64 v3, 0, v1, s[2:3]
	v_pk_mul_f32 v[184:185], v[0:1], v[2:3] op_sel_hi:[0,1]
	v_and_b32_e32 v0, 15, v16
	v_lshlrev_b32_e32 v160, 4, v0
	v_add_u32_e32 v0, s4, v17
	v_ashrrev_i32_e32 v1, 31, v0
	v_lshlrev_b64 v[0:1], 11, v[0:1]
	v_lshl_add_u64 v[170:171], s[58:59], 0, v[0:1]
	v_add3_u32 v0, s94, 64, v17
	v_ashrrev_i32_e32 v1, 31, v0
	v_lshlrev_b64 v[0:1], 11, v[0:1]
	v_lshl_add_u64 v[172:173], s[58:59], 0, v[0:1]
	v_add3_u32 v0, s94, 32, v17
	v_ashrrev_i32_e32 v1, 31, v0
	v_lshlrev_b64 v[0:1], 11, v[0:1]
	v_lshl_add_u64 v[174:175], s[58:59], 0, v[0:1]
	v_add_u32_e32 v0, s94, v17
	v_ashrrev_i32_e32 v1, 31, v0
	v_lshlrev_b64 v[0:1], 11, v[0:1]
	v_add_u32_e32 v198, s18, v38
	s_addk_i32 s18, 0x4000
	v_lshl_add_u64 v[176:177], s[58:59], 0, v[0:1]
	v_mov_b32_e32 v0, 0
	v_pk_mul_f32 v[178:179], v[14:15], v[6:7] op_sel_hi:[1,0]
	v_cmp_eq_u32_e64 s[2:3], 0, v19
	v_add_u32_e32 v165, s18, v38
	v_mov_b32_e32 v1, v0
	v_mov_b32_e32 v2, v0
	v_mov_b32_e32 v3, v0
	v_mov_b32_e32 v4, v0
	v_mov_b32_e32 v5, v0
	v_mov_b32_e32 v6, v0
	v_mov_b32_e32 v7, v0
	v_mov_b32_e32 v8, v0
	v_mov_b32_e32 v9, v0
	v_mov_b32_e32 v10, v0
	v_mov_b32_e32 v11, v0
	v_mov_b32_e32 v12, v0
	v_mov_b32_e32 v13, v0
	v_mov_b32_e32 v14, v0
	v_mov_b32_e32 v15, v0
	v_mov_b32_e32 v16, v0
	v_mov_b32_e32 v17, v0
	v_mov_b32_e32 v18, v0
	v_mov_b32_e32 v19, v0
	v_mov_b32_e32 v20, v0
	v_mov_b32_e32 v21, v0
	v_mov_b32_e32 v22, v0
	v_mov_b32_e32 v23, v0
	v_mov_b32_e32 v24, v0
	v_mov_b32_e32 v25, v0
	v_mov_b32_e32 v26, v0
	v_mov_b32_e32 v27, v0
	v_mov_b32_e32 v28, v0
	v_mov_b32_e32 v29, v0
	v_mov_b32_e32 v30, v0
	v_mov_b32_e32 v31, v0
	v_mov_b32_e32 v32, v0
	v_mov_b32_e32 v33, v0
	v_mov_b32_e32 v34, v0
	v_mov_b32_e32 v35, v0
	v_mov_b32_e32 v36, v0
	v_mov_b32_e32 v37, v0
	v_mov_b32_e32 v38, v0
	v_mov_b32_e32 v39, v0
	v_mov_b32_e32 v40, v0
	v_mov_b32_e32 v41, v0
	v_mov_b32_e32 v42, v0
	v_mov_b32_e32 v43, v0
	v_mov_b32_e32 v44, v0
	v_mov_b32_e32 v45, v0
	v_mov_b32_e32 v46, v0
	v_mov_b32_e32 v47, v0
	v_mov_b32_e32 v48, v0
	v_mov_b32_e32 v49, v0
	v_mov_b32_e32 v50, v0
	v_mov_b32_e32 v51, v0
	v_mov_b32_e32 v52, v0
	v_mov_b32_e32 v53, v0
	v_mov_b32_e32 v54, v0
	v_mov_b32_e32 v55, v0
	v_mov_b32_e32 v56, v0
	v_mov_b32_e32 v57, v0
	v_mov_b32_e32 v58, v0
	v_mov_b32_e32 v59, v0
	v_mov_b32_e32 v60, v0
	v_mov_b32_e32 v61, v0
	v_mov_b32_e32 v62, v0
	v_mov_b32_e32 v63, v0
	s_waitcnt lgkmcnt(0)
	s_barrier
	s_branch .LBB0_1228
